# v53 + ffn_in GEMMs visit column tiles in descending order (the ACT columns ffn_out reads first are the most recently written: better infinity-cache hit order)
# baseline (speedup 1.0000x reference)
;     __device__ __forceinline__ unsigned code(int i, unsigned& ko_) const { Unit u; u.pm = 0; u.pn = 0; u.ko = 0; u.nk = 0; u.ks = 0; const bool ok = next(i, u); ko_ = (unsigned)u.ko; return ok ? (0x80000000u | ((unsigned)u.nk << 16) | ((unsigned)u.pm << 8) | (unsigned)u.pn) : 0u; }
;     __host__ __device__ __forceinline__ bool next(int i, Unit& u) const {
;         const long L = (long)i * G + c; if (L >= nwg) return false;
;         int wgid = (int)L; { const int q = nwg / NXCD, r = nwg % NXCD, xcd = wgid % NXCD, off = wgid / NXCD; wgid = (xcd < r ? xcd * (q + 1) : r * (q + 1) + (xcd - r) * q) + off; }
;         const int nig = WGM * nN, gid = wgid / nig, fm = gid * WGM, gsz = (nM - fm) < WGM ? (nM - fm) : WGM;
;         u.pm = fm + ((wgid % nig) % gsz); u.pn = (wgid % nig) / gsz; u.ko = 0; u.nk = nk; return true;
;     }
;         const int pair = (K / 64) / (nks_ / 2); t1 = ((pair / 2 + 1) / 2) * 2; t2 = pair - t1; }
;     __device__ __forceinline__ unsigned code(int i, unsigned& ko_) const {
;         const int L = i * lat.G + lat.c; if (L < nlat) return lat.code(i, ko_);
;         const int Lp = L - nlat; if (Lp >= nsp) { ko_ = 0u; return 0u; }
;         const int r = Lp / nks, ks = Lp % nks; ko_ = (unsigned)(((ks >> 1) * (t1 + t2) + (ks & 1) * t1) * 64);
;         return 0x80000000u | ((unsigned)ks << 24) | ((unsigned)((ks & 1) ? t2 : t1) << 16) | ((unsigned)(64 + (r & 3)) << 8) | (unsigned)(r >> 2);
;     }
.LBB0_250:
	s_or_b64 exec, exec, s[36:37]
	s_cmpk_lt_i32 s92, 0xbb0
	s_cselect_b64 s[0:1], -1, 0
	v_writelane_b32 v254, s0, 6
	s_ashr_i32 s90, s92, 31
	s_bfe_u32 s2, s92, 0x20001
	v_writelane_b32 v254, s1, 7
	s_lshr_b32 s0, s90, 29
	s_and_b32 s3, s92, 1
	s_add_i32 s0, s92, s0
	s_mul_i32 s2, s2, 22
	s_mul_i32 s4, s3, 12
	s_ashr_i32 s17, s0, 3
	s_and_b32 s0, s0, -8
	s_and_b32 s1, s92, 7
	s_add_i32 s2, s2, s4
	s_sub_i32 s18, s92, s0
	s_and_b32 s0, s92, 0x7fffff00
	s_lshl_b32 s2, s2, 6
	s_lshl_b32 s1, s1, 24
	s_cmp_eq_u32 s3, 0
	s_mov_b32 s3, 0xc0000
	s_cselect_b32 s3, s3, 0xa0000
	s_lshl_b32 s4, s92, 5
	s_and_b32 s4, s4, 0x300
	s_bfe_u32 s5, s92, 0x30005
	s_or_b32 s4, s5, s4
	s_or_b32 s1, s4, s1
	s_or_b32 s3, s1, s3
	s_or_b32 s3, s3, 0x80004000
	s_lshl_b32 s4, s18, 6
	s_lshl_b32 s6, s92, 9
	s_lshl_b32 s5, s92, 2
	s_cmpk_lt_i32 s5, 0x400
	v_writelane_b32 v254, s5, 8
	s_cselect_b64 s[8:9], -1, 0
	v_writelane_b32 v254, s8, 9
	s_lshl_b32 s7, s92, 24
	s_and_b32 s7, s7, 0x3000000
	v_writelane_b32 v254, s9, 10
	s_lshl_b32 s8, s92, 6
	s_bfe_u32 s10, s92, 0x40004
	s_and_b32 s9, s8, 0x300
	s_or_b32 s7, s7, s10
	s_or_b32 s7, s7, s9
	s_add_i32 s5, s92, 0xfffffd00
	v_writelane_b32 v254, s6, 11
	s_and_b32 s6, s6, 0x600
	s_or_b32 s7, s7, 0x80084000
	s_cmpk_lt_i32 s92, 0xcc
	s_cselect_b64 s[10:11], -1, 0
	s_lshl_b32 s12, s94, 8
	s_add_i32 s59, s12, 0
	s_lshl_b32 s12, s94, 12
	v_writelane_b32 v254, s10, 12
	s_add_i32 s12, s12, 0
	s_add_i32 s12, s12, 0x14800
	v_writelane_b32 v254, s11, 13
	v_writelane_b32 v254, s12, 14
	s_add_i32 s12, s92, 0xfffffe00
	s_mul_i32 s9, s18, 25
	v_writelane_b32 v254, s12, 15
	s_lshl_b32 s12, s92, 8
	s_add_i32 s9, s9, 4
	s_add_i32 s10, s92, 0xcc
	s_add_i32 s11, s92, 0xdc
	s_add_i32 s95, s59, 0x10000
	s_lshl_b32 s19, s94, 5
	s_add_i32 s59, s59, 0x14000
	s_and_b32 s12, s12, 0x700
	s_or_b32 s1, s1, 0x80044000
	v_writelane_b32 v254, s12, 16
	s_cmp_lt_i32 s18, 0
	s_movk_i32 s12, 0x177
	v_writelane_b32 v254, s1, 17
	s_mul_i32 s1, s18, 0x41
	s_cselect_b32 s12, s12, 0x176
	s_mul_i32 s12, s18, s12
	s_cselect_b32 s1, s1, s4
	s_movk_i32 s4, 0x61
	s_cselect_b32 s4, s4, 0x60
	s_add_i32 s12, s12, s17
	s_mul_hi_i32 s13, s12, 0x2e8ba2e9
	s_lshr_b32 s14, s13, 31
	s_ashr_i32 s13, s13, 6
	s_add_i32 s13, s13, s14
	s_mul_i32 s14, s13, 0x160
	s_lshl_b32 s13, s13, 3
	s_sub_i32 s15, 0x44, s13
	s_min_u32 s15, s15, 8
	s_sub_i32 s12, s12, s14
	s_cmpk_eq_i32 s0, 0x200
	s_cselect_b32 s2, s2, 0
	s_cselect_b32 s3, s3, 0
	s_add_i32 s0, s1, s17
	s_ashr_i32 s1, s0, 31
	s_lshr_b32 s1, s1, 26
	s_add_i32 s1, s0, s1
	s_and_b32 s14, s1, 0xffc0
	s_sub_i32 s0, s0, s14
	s_bfe_i32 s14, s0, 0x80000
	s_bfe_u32 s14, s14, 0x3000c
	s_add_i32 s14, s0, s14
	s_bfe_i32 s16, s14, 0x80000
	s_and_b32 s14, s14, 0xf8
	s_sub_i32 s0, s0, s14
	s_sext_i32_i8 s0, s0
	s_lshl_b32 s1, s1, 5
	s_sext_i32_i16 s16, s16
	s_and_b32 s1, s1, 0xfffff800
	s_lshl_b32 s0, s0, 8
	s_ashr_i32 s14, s16, 3
	s_add_i32 s0, s0, s1
	s_or_b32 s0, s0, s14
	s_or_b32 s14, s0, 0x80580000
	s_cmpk_lt_u32 s5, 0xc0
	s_mul_i32 s4, s18, s4
	s_cselect_b32 s1, s6, 0
	s_cselect_b32 s5, s7, 0
	s_add_i32 s4, s4, s17
	s_mul_hi_i32 s6, s4, 0x2aaaaaab
	s_lshr_b32 s7, s6, 31
	s_ashr_i32 s6, s6, 4
	s_add_i32 s6, s6, s7
	s_mul_i32 s7, s6, 0x60
	s_sub_i32 s4, s4, s7
	s_bfe_i32 s7, s4, 0x80000
	s_bfe_u32 s7, s7, 0x3000c
	s_add_i32 s7, s4, s7
	s_bfe_i32 s16, s7, 0x80000
	s_and_b32 s7, s7, 0xf8
	s_sub_i32 s4, s4, s7
	s_sext_i32_i8 s4, s4
	s_sext_i32_i16 s16, s16
	s_lshl_b32 s6, s6, 11
	s_lshl_b32 s4, s4, 8
	s_ashr_i32 s7, s16, 3
	s_add_i32 s4, s4, s6
	s_or_b32 s4, s4, s7
	s_or_b32 s4, s4, 0x80200000
	s_cmp_lt_i32 s18, 4
	s_mul_i32 s6, s18, 26
	s_cselect_b32 s6, s6, s9
	s_add_i32 s6, s6, s17
	s_mul_hi_i32 s7, s6, 0x2aaaaaab
	s_lshr_b32 s9, s7, 31
	s_ashr_i32 s7, s7, 2
	s_add_i32 s7, s7, s9
	s_lshl_b32 s9, s7, 3
	s_sub_i32 s16, 0x44, s9
;     __host__ __device__ __forceinline__ bool next(int i, Unit& u) const {
;         const long L = (long)i * G + c; if (L >= nwg) return false;
;         int wgid = (int)L; { const int q = nwg / NXCD, r = nwg % NXCD, xcd = wgid % NXCD, off = wgid / NXCD; wgid = (xcd < r ? xcd * (q + 1) : r * (q + 1) + (xcd - r) * q) + off; }
;         const int nig = WGM * nN, gid = wgid / nig, fm = gid * WGM, gsz = (nM - fm) < WGM ? (nM - fm) : WGM;
;         u.pm = fm + ((wgid % nig) % gsz); u.pn = (wgid % nig) / gsz; u.ko = 0; u.nk = nk; return true;
;     }
	s_mul_i32 s7, s7, 24
	s_min_u32 s16, s16, 8
	s_sub_i32 s6, s6, s7
	s_or_b32 s0, s0, 0x80200000
	v_writelane_b32 v254, s17, 18
	s_cmpk_lt_i32 s92, 0x300
	v_writelane_b32 v254, s0, 19
	s_cselect_b32 s0, 0, s1
	v_writelane_b32 v254, s0, 20
	v_cvt_f32_ubyte0_e32 v1, s15
	v_cvt_f32_i32_e32 v0, s12
	v_writelane_b32 v254, s1, 21
	s_cselect_b32 s0, s4, s5
	v_writelane_b32 v254, s0, 22
	v_writelane_b32 v254, s18, 23
	s_lshr_b32 s0, s18, 31
	v_writelane_b32 v254, s0, 24
	s_mul_i32 s4, s94, 0x21000
	v_writelane_b32 v254, s4, 25
	s_cmpk_lt_i32 s92, 0x200
	v_writelane_b32 v254, s19, 26
	s_mul_hi_u32 s4, s19, 0x1080
	s_cselect_b64 s[0:1], -1, 0
	v_writelane_b32 v254, s4, 27
	v_rcp_iflag_f32_e32 v2, v1
	v_writelane_b32 v254, s0, 28
	s_mov_b64 s[4:5], -1
	s_movk_i32 s73, 0x600
	v_writelane_b32 v254, s1, 29
	s_and_b64 s[0:1], s[0:1], exec
	s_cselect_b32 s0, 0, s2
	v_writelane_b32 v254, s0, 30
	v_mul_f32_e32 v2, v0, v2
	v_trunc_f32_e32 v2, v2
	v_writelane_b32 v254, s1, 31
	s_cselect_b32 s0, s14, s3
	v_writelane_b32 v254, s0, 32
	s_cselect_b32 s0, s14, 0
	v_fma_f32 v0, -v2, v1, v0
	v_cvt_i32_f32_e32 v2, v2
	v_writelane_b32 v254, s0, 33
	s_and_b32 s0, s92, 7
	s_lshl_b32 s0, s0, 3
	s_lshr_b32 s1, s92, 6
	s_add_i32 s0, s0, s1
	s_lshl_b32 s0, s0, 8
	s_bfe_u32 s1, s92, 0x30003
	s_or_b32 s0, s0, s1
	s_or_b32 s0, s0, 0x80580000
	v_writelane_b32 v254, s0, 32
	v_writelane_b32 v254, s0, 33
	s_ashr_i32 s0, s12, 30
	s_or_b32 s2, s0, 1
	v_cmp_ge_f32_e64 s[0:1], |v0|, v1
	s_and_b64 s[0:1], s[0:1], exec
	s_cselect_b32 s0, s2, 0
	v_readfirstlane_b32 s1, v2
	s_add_i32 s0, s1, s0
	v_cvt_f32_ubyte0_e32 v1, s16
	s_sext_i32_i16 s1, s0
	s_mul_i32 s0, s0, s15
	v_cvt_f32_i32_e32 v0, s6
	v_rcp_iflag_f32_e32 v2, v1
	s_sub_i32 s0, s12, s0
	s_sext_i32_i16 s0, s0
	s_add_i32 s13, s13, s0
	s_lshl_b32 s0, s13, 8
	v_mul_f32_e32 v2, v0, v2
	s_or_b32 s0, s0, s1
	v_trunc_f32_e32 v2, v2
	s_or_b32 s0, s0, 0x80200000
	v_fma_f32 v0, -v2, v1, v0
	v_cvt_i32_f32_e32 v2, v2
	s_and_b32 s1, s0, 0xff
	s_sub_i32 s1, 43, s1
	s_andn2_b32 s0, s0, 0xff
	s_or_b32 s0, s0, s1
	v_writelane_b32 v254, s0, 34
	s_ashr_i32 s0, s6, 30
	s_or_b32 s2, s0, 1
	v_cmp_ge_f32_e64 s[0:1], |v0|, v1
	s_and_b64 s[0:1], s[0:1], exec
	s_cselect_b32 s0, s2, 0
	v_readfirstlane_b32 s1, v2
	s_add_i32 s0, s1, s0
	s_sext_i32_i8 s1, s0
	s_mul_i32 s0, s0, s16
	s_sub_i32 s0, s6, s0
	s_sext_i32_i8 s0, s0
	s_add_i32 s9, s9, s0
	s_lshl_b32 s0, s9, 8
	s_or_b32 s0, s0, s1
	s_or_b32 s0, s0, 0x80080000
	v_writelane_b32 v254, s0, 35
	s_ashr_i32 s0, s10, 31
	v_writelane_b32 v254, s0, 36
	s_abs_i32 s0, s10
	v_writelane_b32 v254, s0, 37
	s_ashr_i32 s0, s11, 31
	v_writelane_b32 v254, s0, 38
	s_abs_i32 s0, s11
	v_writelane_b32 v254, s0, 39
	s_or_b32 s0, s8, 7
	v_writelane_b32 v254, s0, 40
	s_add_i32 s0, 0, 0x25ff0
	v_writelane_b32 v254, s0, 41
	s_add_i32 s0, 0, 0x25ff4
	v_writelane_b32 v254, s0, 42
	s_mov_b32 s2, 0
	v_writelane_b32 v254, s2, 43
	v_writelane_b32 v254, s4, 45
	s_movk_i32 s3, 0x1800
	s_mov_b32 s2, s92
	v_writelane_b32 v254, s5, 46
	v_writelane_b32 v254, s96, 47
	s_movk_i32 s66, 0x1080
	v_mov_b32_e32 v193, 0
	v_writelane_b32 v254, s97, 48
	v_writelane_b32 v254, s2, 49
	v_mov_b32_e32 v243, 1
	v_mov_b32_e32 v241, 0x358637bd
	v_writelane_b32 v254, s3, 50
	v_writelane_b32 v254, s94, 51
	s_mov_b32 s68, 0x800000
	s_mov_b32 s79, 0xc00000
	s_movk_i32 s91, 0x1000
	s_mov_b32 s1, 0x42b504f3
	s_mov_b32 s0, 0x1c8ff000
	s_mov_b32 s67, 0x1c07f000
	s_mov_b32 s61, 0x1c907000
	s_mov_b32 s64, 0x1c087000
	s_mov_b32 s69, 0x42ddb3d8
	s_mov_b32 s38, 0x2048f000
	s_mov_b32 s39, 0x1eb1f000
	s_mov_b32 s63, 0x2049f000
	s_mov_b32 s82, 0x1eb37000
	s_mov_b64 s[74:75], 0x20000
	s_mov_b32 s76, 0x3e0293ee
	s_mov_b32 s78, 0x3dd53b94
	s_mov_b64 s[80:81], 0x30000
	s_mov_b32 s41, 0
	v_writelane_b32 v254, s90, 52
	s_waitcnt lgkmcnt(0)
	s_barrier
	s_branch .LBB0_254

;     __host__ __device__ __forceinline__ bool next(int i, Unit& u) const {
;     ...
;         int wgid = (int)L; { const int q = nwg / NXCD, r = nwg % NXCD, xcd = wgid % NXCD, off = wgid / NXCD; wgid = (xcd < r ? xcd * (q + 1) : r * (q + 1) + (xcd - r) * q) + off; }
;         const int nig = WGM * nN, gid = wgid / nig, fm = gid * WGM, gsz = (nM - fm) < WGM ? (nM - fm) : WGM;
;         u.pm = fm + ((wgid % nig) % gsz); u.pn = (wgid % nig) / gsz; u.ko = 0; u.nk = nk; return true;
.LBB0_262:
	s_add_i32 s54, s54, 1
	s_mul_i32 s2, s54, s53
	s_mul_hi_u32 s12, s54, s70
	s_add_i32 s2, s12, s2
	s_mul_i32 s12, s54, s70
	s_add_u32 s12, s12, s92
	s_addc_u32 s13, s2, s90
	v_mov_b64_e32 v[0:1], 0xbaf
	v_cmp_gt_i64_e32 vcc, s[12:13], v[0:1]
	s_mov_b32 s14, 0
	s_cbranch_vccnz .LBB0_264
	s_ashr_i32 s2, s12, 31
	s_lshr_b32 s2, s2, 29
	s_add_i32 s2, s12, s2
	s_ashr_i32 s13, s2, 3
	s_and_b32 s2, s2, -8
	s_sub_i32 s2, s12, s2
	s_cmp_lt_i32 s2, 0
	s_movk_i32 s12, 0x177
	s_cselect_b32 s12, s12, 0x176
	s_mul_i32 s2, s2, s12
	s_add_i32 s2, s2, s13
	s_mul_hi_i32 s12, s2, 0x2e8ba2e9
	s_lshr_b32 s13, s12, 31
	s_ashr_i32 s12, s12, 6
	s_add_i32 s12, s12, s13
	s_lshl_b32 s13, s12, 3
	s_sub_i32 s14, 0x44, s13
	s_min_i32 s14, s14, 8
	s_abs_i32 s15, s14
	v_cvt_f32_u32_e32 v0, s15
	s_sub_i32 s17, 0, s15
	s_mulk_i32 s12, 0x160
	s_sub_i32 s2, s2, s12
	v_rcp_iflag_f32_e32 v0, v0
	s_abs_i32 s12, s2
	s_xor_b32 s16, s2, s14
	s_ashr_i32 s16, s16, 31
	v_mul_f32_e32 v0, 0x4f7ffffe, v0
	v_cvt_u32_f32_e32 v0, v0
	s_nop 0
	v_readfirstlane_b32 s22, v0
	s_mul_i32 s17, s17, s22
	s_mul_hi_u32 s17, s22, s17
	s_add_i32 s22, s22, s17
	s_mul_hi_u32 s17, s12, s22
	s_mul_i32 s22, s17, s15
	s_sub_i32 s12, s12, s22
	s_add_i32 s23, s17, 1
	s_sub_i32 s22, s12, s15
	s_cmp_ge_u32 s12, s15
	s_cselect_b32 s17, s23, s17
	s_cselect_b32 s12, s22, s12
	s_add_i32 s22, s17, 1
	s_cmp_ge_u32 s12, s15
	s_cselect_b32 s12, s22, s17
	s_xor_b32 s12, s12, s16
	s_sub_i32 s12, s12, s16
	s_mul_i32 s14, s12, s14
	s_sub_i32 s2, s2, s14
	s_add_i32 s13, s13, s2
	s_lshl_b32 s2, s13, 8
	s_sub_i32 s12, 43, s12
	s_or_b32 s2, s12, s2
	s_or_b32 s14, s2, 0x80200000

;     __host__ __device__ __forceinline__ bool next(int i, Unit& u) const {
;         const long L = (long)i * G + c; if (L >= nwg) return false;
;         int wgid = (int)L; { const int q = nwg / NXCD, r = nwg % NXCD, xcd = wgid % NXCD, off = wgid / NXCD; wgid = (xcd < r ? xcd * (q + 1) : r * (q + 1) + (xcd - r) * q) + off; }
;         const int nig = WGM * nN, gid = wgid / nig, fm = gid * WGM, gsz = (nM - fm) < WGM ? (nM - fm) : WGM;
;         u.pm = fm + ((wgid % nig) % gsz); u.pn = (wgid % nig) / gsz; u.ko = 0; u.nk = nk; return true;
;     }
.LBB0_1161:
	s_or_b64 exec, exec, s[42:43]
	v_readlane_b32 s4, v254, 45
	s_mov_b64 s[6:7], s[96:97]
	v_readlane_b32 s5, v254, 46
	s_waitcnt lgkmcnt(0)
	s_barrier
	s_load_dwordx2 s[14:15], s[6:7], 0xb8
	s_and_b64 s[4:5], s[4:5], exec
	s_cselect_b32 s4, 0x44, 64
	s_mul_i32 s6, s4, 44
	s_mov_b32 s7, s94
	s_mov_b32 s8, s94
	s_cmp_ge_i32 s92, s6
	s_mov_b32 s10, 0
	v_mbcnt_lo_u32_b32 v0, -1, 0
	v_mbcnt_hi_u32_b32 v0, -1, v0
	s_cbranch_scc1 .LBB0_1163
	s_lshr_b32 s2, s6, 3
	v_readlane_b32 s5, v254, 24
	s_or_b32 s2, s2, s5
	v_readlane_b32 s5, v254, 23
	s_mul_i32 s2, s2, s5
	v_readlane_b32 s5, v254, 18
	s_add_i32 s2, s2, s5
	s_mul_hi_i32 s5, s2, 0x2e8ba2e9
	s_lshr_b32 s9, s5, 31
	s_ashr_i32 s5, s5, 6
	s_add_i32 s5, s5, s9
	s_lshl_b32 s9, s5, 3
	s_sub_i32 s10, s4, s9
	s_min_i32 s10, s10, 8
	s_abs_i32 s11, s10
	v_cvt_f32_u32_e32 v1, s11
	s_sub_i32 s13, 0, s11
	s_mulk_i32 s5, 0x160
	s_sub_i32 s2, s2, s5
	v_rcp_iflag_f32_e32 v1, v1
	s_abs_i32 s5, s2
	s_xor_b32 s12, s2, s10
	s_ashr_i32 s12, s12, 31
	v_mul_f32_e32 v1, 0x4f7ffffe, v1
	v_cvt_u32_f32_e32 v1, v1
	s_nop 0
	v_readfirstlane_b32 s16, v1
	s_mul_i32 s13, s13, s16
	s_mul_hi_u32 s13, s16, s13
	s_add_i32 s16, s16, s13
	s_mul_hi_u32 s13, s5, s16
	s_mul_i32 s16, s13, s11
	s_sub_i32 s5, s5, s16
	s_add_i32 s17, s13, 1
	s_sub_i32 s16, s5, s11
	s_cmp_ge_u32 s5, s11
	s_cselect_b32 s13, s17, s13
	s_cselect_b32 s5, s16, s5
	s_add_i32 s16, s13, 1
	s_cmp_ge_u32 s5, s11
	s_cselect_b32 s5, s16, s13
	s_xor_b32 s5, s5, s12
	s_sub_i32 s5, s5, s12
	s_mul_i32 s10, s5, s10
	s_sub_i32 s2, s2, s10
	s_add_i32 s9, s9, s2
	s_lshl_b32 s2, s9, 8
	s_sub_i32 s5, 43, s5
	s_or_b32 s2, s5, s2
	s_or_b32 s10, s2, 0x80200000

;     __host__ __device__ __forceinline__ bool next(int i, Unit& u) const {
;     ...
;         int wgid = (int)L; { const int q = nwg / NXCD, r = nwg % NXCD, xcd = wgid % NXCD, off = wgid / NXCD; wgid = (xcd < r ? xcd * (q + 1) : r * (q + 1) + (xcd - r) * q) + off; }
;         const int nig = WGM * nN, gid = wgid / nig, fm = gid * WGM, gsz = (nM - fm) < WGM ? (nM - fm) : WGM;
;         u.pm = fm + ((wgid % nig) % gsz); u.pn = (wgid % nig) / gsz; u.ko = 0; u.nk = nk; return true;
.LBB0_1169:
	s_add_i32 s58, s58, 1
	s_mul_i32 s2, s58, s56
	s_mul_hi_u32 s16, s58, s70
	s_add_i32 s2, s16, s2
	s_mul_i32 s16, s58, s70
	s_add_u32 s16, s16, s92
	s_addc_u32 s17, s2, s90
	v_mov_b64_e32 v[0:1], s[6:7]
	v_cmp_ge_i64_e32 vcc, s[16:17], v[0:1]
	s_mov_b32 s18, 0
	s_cbranch_vccnz .LBB0_1171
	s_ashr_i32 s2, s16, 31
	s_lshr_b32 s2, s2, 29
	s_add_i32 s2, s16, s2
	s_ashr_i32 s17, s2, 3
	s_and_b32 s2, s2, -8
	s_sub_i32 s2, s16, s2
	s_lshr_b32 s16, s2, 31
	s_or_b32 s16, s57, s16
	s_mul_i32 s2, s16, s2
	s_add_i32 s2, s2, s17
	s_mul_hi_i32 s16, s2, 0x2e8ba2e9
	s_lshr_b32 s17, s16, 31
	s_ashr_i32 s16, s16, 6
	s_add_i32 s16, s16, s17
	s_lshl_b32 s17, s16, 3
	s_sub_i32 s18, s4, s17
	s_min_i32 s18, s18, 8
	s_abs_i32 s19, s18
	v_cvt_f32_u32_e32 v0, s19
	s_sub_i32 s21, 0, s19
	s_mulk_i32 s16, 0x160
	s_sub_i32 s2, s2, s16
	v_rcp_iflag_f32_e32 v0, v0
	s_abs_i32 s16, s2
	s_xor_b32 s20, s2, s18
	s_ashr_i32 s20, s20, 31
	v_mul_f32_e32 v0, 0x4f7ffffe, v0
	v_cvt_u32_f32_e32 v0, v0
	s_nop 0
	v_readfirstlane_b32 s26, v0
	s_mul_i32 s21, s21, s26
	s_mul_hi_u32 s21, s26, s21
	s_add_i32 s26, s26, s21
	s_mul_hi_u32 s21, s16, s26
	s_mul_i32 s26, s21, s19
	s_sub_i32 s16, s16, s26
	s_add_i32 s27, s21, 1
	s_sub_i32 s26, s16, s19
	s_cmp_ge_u32 s16, s19
	s_cselect_b32 s21, s27, s21
	s_cselect_b32 s16, s26, s16
	s_add_i32 s26, s21, 1
	s_cmp_ge_u32 s16, s19
	s_cselect_b32 s16, s26, s21
	s_xor_b32 s16, s16, s20
	s_sub_i32 s16, s16, s20
	s_mul_i32 s18, s16, s18
	s_sub_i32 s2, s2, s18
	s_add_i32 s2, s2, s17
	s_lshl_b32 s2, s2, 8
	s_sub_i32 s16, 43, s16
	s_or_b32 s2, s16, s2
	s_or_b32 s18, s2, 0x80200000
